# phase_compress K-loop rewritten the same way (27 fragment loads in flight, counted vmcnt)
# speedup vs baseline: 1.1082x; 1.0078x over previous
; __device__ __forceinline__ void phase_compress(const Params& p, int l, char* lds) {
;     ...
;       for (int kk = 0; kk < 8; ++kk) {
;         const int ks = 8 * w + kk, tt = ks >> 1, d0 = (ks & 1) * 32 + q4 * 8;
;         int tok = 16 * m + tt;
;         if (tok > SEQ - 1) tok = SEQ - 1;
;         const h16x8 A = *(const h16x8*)(P + ((size_t)b * SEQ + tok) * IWP + OFF_KVC + st * 64 + d0);
; #pragma unroll
;         for (int nt = 0; nt < 8; ++nt) {
;           const h16x8 B = *(const h16x8*)(W1t + (size_t)(nt * 16 + col) * 2048 + ks * 32 + q4 * 8);
;           acc[nt] = __builtin_amdgcn_mfma_f32_16x16x32_f16(A, B, acc[nt], 0, 0, 0);
;         }
;       }
.LBB0_630:
	v_ashrrev_i32_e32 v96, 1, v53
	v_add_u32_e32 v96, v96, v51
	v_min_i32_e32 v96, 0x1fff, v96
	v_ashrrev_i32_e32 v97, 31, v96
	v_lshl_add_u64 v[96:97], s[8:9], 0, v[96:97]
	v_mov_b64_e32 v[98:99], s[0:1]
	v_mad_u64_u32 v[100:101], s[18:19], v96, s85, v[98:99]
	v_mad_i32_i24 v101, v97, s85, v101
	v_lshl_add_u64 v[100:101], v[100:101], 0, s[92:93]
	v_lshl_add_u64 v[100:101], v[100:101], 0, v[0:1]
	v_add_co_u32_e32 v100, vcc, s64, v100
	s_nop 1
	v_addc_co_u32_e32 v101, vcc, 0, v101, vcc
	global_load_dwordx4 v[126:129], v[100:101], off
	v_add_u32_e32 v96, 1, v53
	v_ashrrev_i32_e32 v96, 1, v96
	v_add_u32_e32 v96, v96, v51
	v_min_i32_e32 v96, 0x1fff, v96
	v_ashrrev_i32_e32 v97, 31, v96
	v_lshl_add_u64 v[96:97], s[8:9], 0, v[96:97]
	v_mad_u64_u32 v[102:103], s[18:19], v96, s85, v[54:55]
	v_mad_i32_i24 v103, v97, s85, v103
	v_add_co_u32_e32 v102, vcc, s64, v102
	s_nop 1
	v_addc_co_u32_e32 v103, vcc, 0, v103, vcc
	global_load_dwordx4 v[130:133], v[102:103], off offset:64
	v_add_u32_e32 v96, 2, v53
	v_ashrrev_i32_e32 v96, 1, v96
	v_add_u32_e32 v96, v96, v51
	v_min_i32_e32 v96, 0x1fff, v96
	v_ashrrev_i32_e32 v97, 31, v96
	v_lshl_add_u64 v[96:97], s[8:9], 0, v[96:97]
	v_mov_b64_e32 v[98:99], s[0:1]
	v_mad_u64_u32 v[104:105], s[18:19], v96, s85, v[98:99]
	v_mad_i32_i24 v105, v97, s85, v105
	v_lshl_add_u64 v[104:105], v[104:105], 0, s[92:93]
	v_lshl_add_u64 v[104:105], v[104:105], 0, v[0:1]
	v_add_co_u32_e32 v104, vcc, s64, v104
	s_nop 1
	v_addc_co_u32_e32 v105, vcc, 0, v105, vcc
	global_load_dwordx4 v[134:137], v[104:105], off
	v_add_u32_e32 v96, 3, v53
	v_ashrrev_i32_e32 v96, 1, v96
	v_add_u32_e32 v96, v96, v51
	v_min_i32_e32 v96, 0x1fff, v96
	v_ashrrev_i32_e32 v97, 31, v96
	v_lshl_add_u64 v[96:97], s[8:9], 0, v[96:97]
	v_mad_u64_u32 v[106:107], s[18:19], v96, s85, v[54:55]
	v_mad_i32_i24 v107, v97, s85, v107
	v_add_co_u32_e32 v106, vcc, s64, v106
	s_nop 1
	v_addc_co_u32_e32 v107, vcc, 0, v107, vcc
	v_lshl_add_u64 v[108:109], v[56:57], 0, s[12:13]
	s_mov_b32 s18, 0xe439000
	v_add_co_u32_e32 v110, vcc, s18, v108
	s_nop 1
	v_addc_co_u32_e32 v111, vcc, 0, v109, vcc
	s_mov_b32 s18, 0xe449000
	v_add_co_u32_e32 v112, vcc, s18, v108
	s_nop 1
	v_addc_co_u32_e32 v113, vcc, 0, v109, vcc
	s_mov_b32 s18, 0xe459000
	v_add_co_u32_e32 v114, vcc, s18, v108
	s_nop 1
	v_addc_co_u32_e32 v115, vcc, 0, v109, vcc
	s_mov_b32 s18, 0xe469000
	v_add_co_u32_e32 v116, vcc, s18, v108
	s_nop 1
	v_addc_co_u32_e32 v117, vcc, 0, v109, vcc
	s_mov_b32 s18, 0xe479000
	v_add_co_u32_e32 v118, vcc, s18, v108
	s_nop 1
	v_addc_co_u32_e32 v119, vcc, 0, v109, vcc
	s_mov_b32 s18, 0xe489000
	v_add_co_u32_e32 v120, vcc, s18, v108
	s_nop 1
	v_addc_co_u32_e32 v121, vcc, 0, v109, vcc
	s_mov_b32 s18, 0xe499000
	v_add_co_u32_e32 v122, vcc, s18, v108
	s_nop 1
	v_addc_co_u32_e32 v123, vcc, 0, v109, vcc
	s_mov_b32 s18, 0xe4a9000
	v_add_co_u32_e32 v124, vcc, s18, v108
	s_nop 1
	v_addc_co_u32_e32 v125, vcc, 0, v109, vcc
	global_load_dwordx4 v[152:155], v[110:111], off
	global_load_dwordx4 v[156:159], v[112:113], off
	global_load_dwordx4 v[160:163], v[114:115], off
	global_load_dwordx4 v[164:167], v[116:117], off
	global_load_dwordx4 v[168:171], v[118:119], off
	global_load_dwordx4 v[172:175], v[120:121], off
	global_load_dwordx4 v[176:179], v[122:123], off
	global_load_dwordx4 v[180:183], v[124:125], off
	global_load_dwordx4 v[202:205], v[110:111], off offset:64
	global_load_dwordx4 v[206:209], v[112:113], off offset:64
	global_load_dwordx4 v[210:213], v[114:115], off offset:64
	global_load_dwordx4 v[214:217], v[116:117], off offset:64
	global_load_dwordx4 v[218:221], v[118:119], off offset:64
	global_load_dwordx4 v[222:225], v[120:121], off offset:64
	global_load_dwordx4 v[226:229], v[122:123], off offset:64
	global_load_dwordx4 v[230:233], v[124:125], off offset:64
	global_load_dwordx4 v[234:237], v[110:111], off offset:128
	global_load_dwordx4 v[238:241], v[112:113], off offset:128
	global_load_dwordx4 v[242:245], v[114:115], off offset:128
	global_load_dwordx4 v[246:249], v[116:117], off offset:128
	global_load_dwordx4 v[250:253], v[118:119], off offset:128
	global_load_dwordx4 v[184:187], v[120:121], off offset:128
	global_load_dwordx4 v[138:141], v[122:123], off offset:128
	global_load_dwordx4 v[96:99], v[124:125], off offset:128
	s_waitcnt vmcnt(16)
	v_mfma_f32_16x16x32_f16 v[30:33], v[126:129], v[152:155], v[30:33]
	v_mfma_f32_16x16x32_f16 v[26:29], v[126:129], v[156:159], v[26:29]
	v_mfma_f32_16x16x32_f16 v[22:25], v[126:129], v[160:163], v[22:25]
	v_mfma_f32_16x16x32_f16 v[18:21], v[126:129], v[164:167], v[18:21]
	v_mfma_f32_16x16x32_f16 v[14:17], v[126:129], v[168:171], v[14:17]
	v_mfma_f32_16x16x32_f16 v[10:13], v[126:129], v[172:175], v[10:13]
	v_mfma_f32_16x16x32_f16 v[6:9], v[126:129], v[176:179], v[6:9]
	v_mfma_f32_16x16x32_f16 v[2:5], v[126:129], v[180:183], v[2:5]
	global_load_dwordx4 v[126:129], v[106:107], off offset:64
	global_load_dwordx4 v[152:155], v[110:111], off offset:192
	global_load_dwordx4 v[156:159], v[112:113], off offset:192
	global_load_dwordx4 v[160:163], v[114:115], off offset:192
	global_load_dwordx4 v[164:167], v[116:117], off offset:192
	global_load_dwordx4 v[168:171], v[118:119], off offset:192
	global_load_dwordx4 v[172:175], v[120:121], off offset:192
	global_load_dwordx4 v[176:179], v[122:123], off offset:192
	global_load_dwordx4 v[180:183], v[124:125], off offset:192
	s_waitcnt vmcnt(17)
; __device__ __forceinline__ void phase_compress(const Params& p, int l, char* lds) {
;     ...
;         for (int nt = 0; nt < 8; ++nt) {
;           const h16x8 B = *(const h16x8*)(W1t + (size_t)(nt * 16 + col) * 2048 + ks * 32 + q4 * 8);
;           acc[nt] = __builtin_amdgcn_mfma_f32_16x16x32_f16(A, B, acc[nt], 0, 0, 0);
;         }
;       }
; #pragma unroll
;       for (int nt = 0; nt < 8; ++nt)
; #pragma unroll
;         for (int j = 0; j < 4; ++j) red[(w * 16 + q4 * 4 + j) * RPAD + nt * 16 + col] = acc[nt][j];
;     }
;     __syncthreads();
;     {
;       const int row = tid >> 5, c4 = (tid & 31) * 4;
;       float4 sum = *(const float4*)(b1 + c4);
; #pragma unroll
;       for (int ww = 0; ww < 8; ++ww) {
;         const float4 v = *(const float4*)(red + (ww * 16 + row) * RPAD + c4);
;         sum.x += v.x; sum.y += v.y; sum.z += v.z; sum.w += v.w;
;       }
;       *(h16x4*)(hid + row * HPAD + c4) = pack4(gelu_tanh(sum.x), gelu_tanh(sum.y), gelu_tanh(sum.z), gelu_tanh(sum.w));
	v_mfma_f32_16x16x32_f16 v[30:33], v[130:133], v[202:205], v[30:33]
	v_mfma_f32_16x16x32_f16 v[26:29], v[130:133], v[206:209], v[26:29]
	v_mfma_f32_16x16x32_f16 v[22:25], v[130:133], v[210:213], v[22:25]
	v_mfma_f32_16x16x32_f16 v[18:21], v[130:133], v[214:217], v[18:21]
	v_mfma_f32_16x16x32_f16 v[14:17], v[130:133], v[218:221], v[14:17]
	v_mfma_f32_16x16x32_f16 v[10:13], v[130:133], v[222:225], v[10:13]
	v_mfma_f32_16x16x32_f16 v[6:9], v[130:133], v[226:229], v[6:9]
	v_mfma_f32_16x16x32_f16 v[2:5], v[130:133], v[230:233], v[2:5]
	s_waitcnt vmcnt(9)
	v_mfma_f32_16x16x32_f16 v[30:33], v[134:137], v[234:237], v[30:33]
	v_mfma_f32_16x16x32_f16 v[26:29], v[134:137], v[238:241], v[26:29]
	v_mfma_f32_16x16x32_f16 v[22:25], v[134:137], v[242:245], v[22:25]
	v_mfma_f32_16x16x32_f16 v[18:21], v[134:137], v[246:249], v[18:21]
	v_mfma_f32_16x16x32_f16 v[14:17], v[134:137], v[250:253], v[14:17]
	v_mfma_f32_16x16x32_f16 v[10:13], v[134:137], v[184:187], v[10:13]
	v_mfma_f32_16x16x32_f16 v[6:9], v[134:137], v[138:141], v[6:9]
	v_mfma_f32_16x16x32_f16 v[2:5], v[134:137], v[96:99], v[2:5]
	s_waitcnt vmcnt(0)
	v_mfma_f32_16x16x32_f16 v[30:33], v[126:129], v[152:155], v[30:33]
	v_mfma_f32_16x16x32_f16 v[26:29], v[126:129], v[156:159], v[26:29]
	v_mfma_f32_16x16x32_f16 v[22:25], v[126:129], v[160:163], v[22:25]
	v_mfma_f32_16x16x32_f16 v[18:21], v[126:129], v[164:167], v[18:21]
	v_mfma_f32_16x16x32_f16 v[14:17], v[126:129], v[168:171], v[14:17]
	v_mfma_f32_16x16x32_f16 v[10:13], v[126:129], v[172:175], v[10:13]
	v_mfma_f32_16x16x32_f16 v[6:9], v[126:129], v[176:179], v[6:9]
	v_mfma_f32_16x16x32_f16 v[2:5], v[126:129], v[180:183], v[2:5]
	v_add_u32_e32 v53, 4, v53
	s_add_u32 s12, s12, 0x100
	s_addc_u32 s13, s13, 0
	s_cmpk_eq_i32 s12, 0x200
	s_cbranch_scc0 .LBB0_630
	s_or_b32 s8, s17, s2
	s_ashr_i32 s9, s15, 31
	s_lshl_b32 s92, s8, 7
	s_add_u32 s15, s82, s15
	s_addc_u32 s9, s83, s9
	s_lshl_b64 s[12:13], s[92:93], 2
	s_add_u32 s12, s15, s12
	ds_write2_b32 v84, v30, v26 offset1:16
	ds_write2_b32 v84, v31, v27 offset0:132 offset1:148
	v_add_u32_e32 v26, 0x400, v84
	s_addc_u32 s13, s9, s13
	v_mov_b32_e32 v51, v1
	ds_write2_b32 v26, v32, v28 offset0:8 offset1:24
	ds_write2_b32 v26, v33, v29 offset0:140 offset1:156
	ds_write2_b32 v84, v22, v18 offset0:32 offset1:48
	ds_write2_b32 v84, v23, v19 offset0:164 offset1:180
	ds_write2_b32 v26, v24, v20 offset0:40 offset1:56
	ds_write2_b32 v26, v25, v21 offset0:172 offset1:188
	ds_write2_b32 v84, v14, v10 offset0:64 offset1:80
	ds_write2_b32 v84, v15, v11 offset0:196 offset1:212
	ds_write2_b32 v26, v16, v12 offset0:72 offset1:88
	ds_write2_b32 v26, v17, v13 offset0:204 offset1:220
	ds_write2_b32 v84, v6, v2 offset0:96 offset1:112
	ds_write2_b32 v84, v7, v3 offset0:228 offset1:244
	ds_write2_b32 v26, v8, v4 offset0:104 offset1:120
	ds_write2_b32 v26, v9, v5 offset0:236 offset1:252
	v_lshl_add_u64 v[2:3], s[12:13], 0, v[50:51]
	s_mov_b32 s9, 0xa010000
	v_add_co_u32_e32 v2, vcc, s9, v2
	s_waitcnt lgkmcnt(0)
	s_nop 0
	v_addc_co_u32_e32 v3, vcc, 0, v3, vcc
	s_barrier
	global_load_dwordx4 v[2:5], v[2:3], off
	ds_read_b128 v[6:9], v85
	ds_read_b128 v[10:13], v85 offset:8448
	ds_read_b128 v[14:17], v85 offset:16896
	ds_read_b128 v[18:21], v85 offset:25344
	ds_read_b128 v[22:25], v85 offset:33792
	ds_read_b128 v[26:29], v85 offset:42240
	ds_read_b128 v[30:33], v85 offset:50688
	ds_read_b128 v[34:37], v85 offset:59136
	s_waitcnt vmcnt(0) lgkmcnt(7)
	v_add_f32_e32 v2, v2, v6
	s_waitcnt lgkmcnt(6)
	v_add_f32_e32 v2, v2, v10
	s_waitcnt lgkmcnt(5)
	v_add_f32_e32 v2, v2, v14
	s_waitcnt lgkmcnt(4)
	v_add_f32_e32 v2, v2, v18
	s_waitcnt lgkmcnt(3)
	v_add_f32_e32 v2, v2, v22
	s_waitcnt lgkmcnt(2)
	v_add_f32_e32 v2, v2, v26
	s_waitcnt lgkmcnt(1)
	v_add_f32_e32 v2, v2, v30
	s_waitcnt lgkmcnt(0)
	v_add_f32_e32 v2, v2, v34
	v_mul_f32_e32 v6, 0x3d372713, v2
	v_mul_f32_e32 v6, v2, v6
	v_fma_f32 v6, v2, v6, v2
	v_mul_f32_e32 v6, 0x3f4c422a, v6
	v_cmp_nlt_f32_e64 s[12:13], |v6|, s65
	s_and_saveexec_b64 s[18:19], s[12:13]
	s_xor_b64 s[12:13], exec, s[18:19]
	s_cbranch_execz .LBB0_633
	v_add_f32_e64 v10, |v6|, |v6|
	v_mul_f32_e32 v14, 0x3fb8aa3b, v10
	v_rndne_f32_e32 v18, v14
	v_sub_f32_e32 v22, v14, v18
	v_fma_f32 v14, v10, s66, -v14
	v_fmac_f32_e32 v14, 0x32a5705f, v10
	v_add_f32_e32 v14, v22, v14
	v_cvt_i32_f32_e32 v18, v18
	v_exp_f32_e32 v14, v14
	v_cmp_ngt_f32_e32 vcc, s78, v10
	v_ldexp_f32 v14, v14, v18
	s_nop 0
	v_cndmask_b32_e32 v14, 0, v14, vcc
	v_cmp_nlt_f32_e32 vcc, s79, v10
	s_nop 1
	v_cndmask_b32_e32 v10, v201, v14, vcc
	v_add_f32_e32 v10, 1.0, v10
	v_rcp_f32_e32 v10, v10
	s_nop 0
	v_fma_f32 v10, v10, -2.0, 1.0
